# phase 0 modulation GEMV: all 32 weight loads of an item in flight (was 8 then drain)
# speedup vs baseline: 1.0225x; 1.0019x over previous
.LBB0_8:
	s_and_b32 s29, s28, 31
	s_waitcnt lgkmcnt(0)
	s_barrier
	s_and_saveexec_b64 s[20:21], s[4:5]
	s_cbranch_execz .Lp0_noc
	v_lshl_or_b32 v2, s29, 5, v12
	s_and_saveexec_b64 s[22:23], s[6:7]
	s_xor_b64 s[22:23], exec, s[22:23]
	s_load_dwordx2 s[30:31], s[8:9], 0x28
	v_or_b32_e32 v4, v2, v13
	v_ashrrev_i32_e32 v5, 31, v4
	s_waitcnt lgkmcnt(0)
	v_lshl_add_u64 v[4:5], v[4:5], 2, s[30:31]
	s_andn2_saveexec_b64 s[22:23], s[22:23]
	s_load_dwordx2 s[30:31], s[8:9], 0x30
	v_lshlrev_b32_e32 v2, 2, v2
	s_waitcnt lgkmcnt(0)
	v_lshl_add_u64 v[4:5], s[30:31], 0, v[2:3]
	s_or_b64 exec, exec, s[22:23]
	global_load_dword v2, v[4:5], off
.Lp0_noc:
	s_or_b64 exec, exec, s[20:21]
	s_ashr_i32 s15, s28, 5
	s_mul_hi_i32 s16, s15, 0x2aaaaaab
	s_lshr_b32 s17, s16, 31
	s_lshr_b32 s16, s16, 1
	s_add_i32 s16, s16, s17
	s_mul_i32 s16, s16, 12
	s_sub_i32 s15, s15, s16
	v_lshl_add_u32 v10, s15, 9, v1
	s_mul_hi_i32 s16, s28, 0x2aaaaaab
	s_lshr_b32 s17, s16, 31
	s_ashr_i32 s16, s16, 6
	s_add_i32 s16, s16, s17
	v_lshlrev_b32_e32 v10, 2, v10
	s_mul_i32 s14, s29, 0xc0000
	s_mul_i32 s17, s16, 0x1800000
	s_mul_hi_i32 s15, s16, 0x1800000
	s_add_u32 s14, s17, s14
	s_addc_u32 s15, s15, 0
	s_add_u32 s14, s12, s14
	s_addc_u32 s15, s13, s15
	global_load_dword v16, v10, s[14:15] nt
	s_add_u32 s14, s14, 0x6000
	s_addc_u32 s15, s15, 0
	global_load_dword v17, v10, s[14:15] nt
	s_add_u32 s14, s14, 0x6000
	s_addc_u32 s15, s15, 0
	global_load_dword v18, v10, s[14:15] nt
	s_add_u32 s14, s14, 0x6000
	s_addc_u32 s15, s15, 0
	global_load_dword v19, v10, s[14:15] nt
	s_add_u32 s14, s14, 0x6000
	s_addc_u32 s15, s15, 0
	global_load_dword v20, v10, s[14:15] nt
	s_add_u32 s14, s14, 0x6000
	s_addc_u32 s15, s15, 0
	global_load_dword v21, v10, s[14:15] nt
	s_add_u32 s14, s14, 0x6000
	s_addc_u32 s15, s15, 0
	global_load_dword v22, v10, s[14:15] nt
	s_add_u32 s14, s14, 0x6000
	s_addc_u32 s15, s15, 0
	global_load_dword v23, v10, s[14:15] nt
	s_add_u32 s14, s14, 0x6000
	s_addc_u32 s15, s15, 0
	global_load_dword v24, v10, s[14:15] nt
	s_add_u32 s14, s14, 0x6000
	s_addc_u32 s15, s15, 0
	global_load_dword v25, v10, s[14:15] nt
	s_add_u32 s14, s14, 0x6000
	s_addc_u32 s15, s15, 0
	global_load_dword v26, v10, s[14:15] nt
	s_add_u32 s14, s14, 0x6000
	s_addc_u32 s15, s15, 0
	global_load_dword v27, v10, s[14:15] nt
	s_add_u32 s14, s14, 0x6000
	s_addc_u32 s15, s15, 0
	global_load_dword v28, v10, s[14:15] nt
	s_add_u32 s14, s14, 0x6000
	s_addc_u32 s15, s15, 0
	global_load_dword v29, v10, s[14:15] nt
	s_add_u32 s14, s14, 0x6000
	s_addc_u32 s15, s15, 0
	global_load_dword v30, v10, s[14:15] nt
	s_add_u32 s14, s14, 0x6000
	s_addc_u32 s15, s15, 0
	global_load_dword v31, v10, s[14:15] nt
	s_add_u32 s14, s14, 0x6000
	s_addc_u32 s15, s15, 0
	global_load_dword v32, v10, s[14:15] nt
	s_add_u32 s14, s14, 0x6000
	s_addc_u32 s15, s15, 0
	global_load_dword v33, v10, s[14:15] nt
	s_add_u32 s14, s14, 0x6000
	s_addc_u32 s15, s15, 0
	global_load_dword v34, v10, s[14:15] nt
	s_add_u32 s14, s14, 0x6000
	s_addc_u32 s15, s15, 0
	global_load_dword v35, v10, s[14:15] nt
	s_add_u32 s14, s14, 0x6000
	s_addc_u32 s15, s15, 0
	global_load_dword v36, v10, s[14:15] nt
	s_add_u32 s14, s14, 0x6000
	s_addc_u32 s15, s15, 0
	global_load_dword v37, v10, s[14:15] nt
	s_add_u32 s14, s14, 0x6000
	s_addc_u32 s15, s15, 0
	global_load_dword v38, v10, s[14:15] nt
	s_add_u32 s14, s14, 0x6000
	s_addc_u32 s15, s15, 0
	global_load_dword v39, v10, s[14:15] nt
	s_add_u32 s14, s14, 0x6000
	s_addc_u32 s15, s15, 0
	global_load_dword v40, v10, s[14:15] nt
	s_add_u32 s14, s14, 0x6000
	s_addc_u32 s15, s15, 0
	global_load_dword v41, v10, s[14:15] nt
	s_add_u32 s14, s14, 0x6000
	s_addc_u32 s15, s15, 0
	global_load_dword v42, v10, s[14:15] nt
	s_add_u32 s14, s14, 0x6000
	s_addc_u32 s15, s15, 0
	global_load_dword v43, v10, s[14:15] nt
	s_add_u32 s14, s14, 0x6000
	s_addc_u32 s15, s15, 0
	global_load_dword v44, v10, s[14:15] nt
	s_add_u32 s14, s14, 0x6000
	s_addc_u32 s15, s15, 0
	global_load_dword v45, v10, s[14:15] nt
	s_add_u32 s14, s14, 0x6000
	s_addc_u32 s15, s15, 0
	global_load_dword v46, v10, s[14:15] nt
	s_add_u32 s14, s14, 0x6000
	s_addc_u32 s15, s15, 0
	global_load_dword v47, v10, s[14:15] nt
	v_mov_b32_e32 v100, 0
	v_mov_b32_e32 v101, 0
	v_mov_b32_e32 v102, 0
	v_mov_b32_e32 v103, 0
	v_mov_b32_e32 v104, 0
	s_and_saveexec_b64 s[20:21], s[4:5]
	s_cbranch_execz .Lp0_nosilu
	s_waitcnt vmcnt(32)
	v_mul_f32_e32 v4, 0xbfb8aa3b, v2
	v_rndne_f32_e32 v5, v4
	v_fma_f32 v6, v2, s3, -v4
	v_sub_f32_e32 v4, v4, v5
	v_fmac_f32_e32 v6, 0xb2a5705f, v2
	v_add_f32_e32 v4, v4, v6
	v_cvt_i32_f32_e32 v5, v5
	v_exp_f32_e32 v4, v4
	v_cmp_nlt_f32_e32 vcc, s18, v2
	v_ldexp_f32 v4, v4, v5
	s_nop 0
	v_cndmask_b32_e32 v4, 0, v4, vcc
	v_cmp_ngt_f32_e32 vcc, s19, v2
	s_nop 1
	v_cndmask_b32_e32 v4, v15, v4, vcc
	v_add_f32_e32 v4, 1.0, v4
	v_div_scale_f32 v5, s[22:23], v4, v4, v2
	v_rcp_f32_e32 v6, v5
	v_div_scale_f32 v7, vcc, v2, v4, v2
	v_fma_f32 v8, -v5, v6, 1.0
	v_fmac_f32_e32 v6, v8, v6
	v_mul_f32_e32 v8, v7, v6
	v_fma_f32 v9, -v5, v8, v7
	v_fmac_f32_e32 v8, v9, v6
	v_fma_f32 v5, -v5, v8, v7
	v_div_fmas_f32 v5, v5, v6, v8
	v_div_fixup_f32 v2, v5, v4, v2
	ds_write_b32 v14, v2
.Lp0_nosilu:
	s_or_b64 exec, exec, s[20:21]
	s_waitcnt lgkmcnt(0)
	s_barrier
	ds_read_b128 v[48:51], v3 offset:0
	ds_read_b128 v[52:55], v3 offset:16
	ds_read_b128 v[56:59], v3 offset:128
	ds_read_b128 v[60:63], v3 offset:144
	ds_read_b128 v[64:67], v3 offset:256
	ds_read_b128 v[68:71], v3 offset:272
	ds_read_b128 v[72:75], v3 offset:384
	ds_read_b128 v[76:79], v3 offset:400
	ds_read_b128 v[80:83], v3 offset:512
	ds_read_b128 v[84:87], v3 offset:528
	s_waitcnt lgkmcnt(0)
	s_waitcnt vmcnt(31)
	v_fmac_f32_e32 v100, v16, v48
	v_fmac_f32_e32 v101, v16, v56
	v_fmac_f32_e32 v102, v16, v64
	v_fmac_f32_e32 v103, v16, v72
	v_fmac_f32_e32 v104, v16, v80
	s_waitcnt vmcnt(30)
	v_fmac_f32_e32 v100, v17, v49
	v_fmac_f32_e32 v101, v17, v57
	v_fmac_f32_e32 v102, v17, v65
	v_fmac_f32_e32 v103, v17, v73
	v_fmac_f32_e32 v104, v17, v81
	s_waitcnt vmcnt(29)
	v_fmac_f32_e32 v100, v18, v50
	v_fmac_f32_e32 v101, v18, v58
	v_fmac_f32_e32 v102, v18, v66
	v_fmac_f32_e32 v103, v18, v74
	v_fmac_f32_e32 v104, v18, v82
	s_waitcnt vmcnt(28)
	v_fmac_f32_e32 v100, v19, v51
	v_fmac_f32_e32 v101, v19, v59
	v_fmac_f32_e32 v102, v19, v67
	v_fmac_f32_e32 v103, v19, v75
	v_fmac_f32_e32 v104, v19, v83
	s_waitcnt vmcnt(27)
	v_fmac_f32_e32 v100, v20, v52
	v_fmac_f32_e32 v101, v20, v60
	v_fmac_f32_e32 v102, v20, v68
	v_fmac_f32_e32 v103, v20, v76
	v_fmac_f32_e32 v104, v20, v84
	s_waitcnt vmcnt(26)
	v_fmac_f32_e32 v100, v21, v53
	v_fmac_f32_e32 v101, v21, v61
	v_fmac_f32_e32 v102, v21, v69
	v_fmac_f32_e32 v103, v21, v77
	v_fmac_f32_e32 v104, v21, v85
	s_waitcnt vmcnt(25)
	v_fmac_f32_e32 v100, v22, v54
	v_fmac_f32_e32 v101, v22, v62
	v_fmac_f32_e32 v102, v22, v70
	v_fmac_f32_e32 v103, v22, v78
	v_fmac_f32_e32 v104, v22, v86
	s_waitcnt vmcnt(24)
	v_fmac_f32_e32 v100, v23, v55
	v_fmac_f32_e32 v101, v23, v63
	v_fmac_f32_e32 v102, v23, v71
	v_fmac_f32_e32 v103, v23, v79
	v_fmac_f32_e32 v104, v23, v87
	ds_read_b128 v[48:51], v3 offset:32
	ds_read_b128 v[52:55], v3 offset:48
	ds_read_b128 v[56:59], v3 offset:160
	ds_read_b128 v[60:63], v3 offset:176
	ds_read_b128 v[64:67], v3 offset:288
	ds_read_b128 v[68:71], v3 offset:304
	ds_read_b128 v[72:75], v3 offset:416
	ds_read_b128 v[76:79], v3 offset:432
	ds_read_b128 v[80:83], v3 offset:544
	ds_read_b128 v[84:87], v3 offset:560
	s_waitcnt lgkmcnt(0)
	s_waitcnt vmcnt(23)
	v_fmac_f32_e32 v100, v24, v48
	v_fmac_f32_e32 v101, v24, v56
	v_fmac_f32_e32 v102, v24, v64
	v_fmac_f32_e32 v103, v24, v72
	v_fmac_f32_e32 v104, v24, v80
	s_waitcnt vmcnt(22)
	v_fmac_f32_e32 v100, v25, v49
	v_fmac_f32_e32 v101, v25, v57
	v_fmac_f32_e32 v102, v25, v65
	v_fmac_f32_e32 v103, v25, v73
	v_fmac_f32_e32 v104, v25, v81
	s_waitcnt vmcnt(21)
	v_fmac_f32_e32 v100, v26, v50
	v_fmac_f32_e32 v101, v26, v58
	v_fmac_f32_e32 v102, v26, v66
	v_fmac_f32_e32 v103, v26, v74
	v_fmac_f32_e32 v104, v26, v82
	s_waitcnt vmcnt(20)
	v_fmac_f32_e32 v100, v27, v51
	v_fmac_f32_e32 v101, v27, v59
	v_fmac_f32_e32 v102, v27, v67
	v_fmac_f32_e32 v103, v27, v75
	v_fmac_f32_e32 v104, v27, v83
	s_waitcnt vmcnt(19)
	v_fmac_f32_e32 v100, v28, v52
	v_fmac_f32_e32 v101, v28, v60
	v_fmac_f32_e32 v102, v28, v68
	v_fmac_f32_e32 v103, v28, v76
	v_fmac_f32_e32 v104, v28, v84
	s_waitcnt vmcnt(18)
	v_fmac_f32_e32 v100, v29, v53
	v_fmac_f32_e32 v101, v29, v61
	v_fmac_f32_e32 v102, v29, v69
	v_fmac_f32_e32 v103, v29, v77
	v_fmac_f32_e32 v104, v29, v85
	s_waitcnt vmcnt(17)
	v_fmac_f32_e32 v100, v30, v54
	v_fmac_f32_e32 v101, v30, v62
	v_fmac_f32_e32 v102, v30, v70
	v_fmac_f32_e32 v103, v30, v78
	v_fmac_f32_e32 v104, v30, v86
	s_waitcnt vmcnt(16)
	v_fmac_f32_e32 v100, v31, v55
	v_fmac_f32_e32 v101, v31, v63
	v_fmac_f32_e32 v102, v31, v71
	v_fmac_f32_e32 v103, v31, v79
	v_fmac_f32_e32 v104, v31, v87
	ds_read_b128 v[48:51], v3 offset:64
	ds_read_b128 v[52:55], v3 offset:80
	ds_read_b128 v[56:59], v3 offset:192
	ds_read_b128 v[60:63], v3 offset:208
	ds_read_b128 v[64:67], v3 offset:320
	ds_read_b128 v[68:71], v3 offset:336
	ds_read_b128 v[72:75], v3 offset:448
	ds_read_b128 v[76:79], v3 offset:464
	ds_read_b128 v[80:83], v3 offset:576
	ds_read_b128 v[84:87], v3 offset:592
	s_waitcnt lgkmcnt(0)
	s_waitcnt vmcnt(15)
	v_fmac_f32_e32 v100, v32, v48
	v_fmac_f32_e32 v101, v32, v56
	v_fmac_f32_e32 v102, v32, v64
	v_fmac_f32_e32 v103, v32, v72
	v_fmac_f32_e32 v104, v32, v80
	s_waitcnt vmcnt(14)
	v_fmac_f32_e32 v100, v33, v49
	v_fmac_f32_e32 v101, v33, v57
	v_fmac_f32_e32 v102, v33, v65
	v_fmac_f32_e32 v103, v33, v73
	v_fmac_f32_e32 v104, v33, v81
	s_waitcnt vmcnt(13)
	v_fmac_f32_e32 v100, v34, v50
	v_fmac_f32_e32 v101, v34, v58
	v_fmac_f32_e32 v102, v34, v66
	v_fmac_f32_e32 v103, v34, v74
	v_fmac_f32_e32 v104, v34, v82
	s_waitcnt vmcnt(12)
	v_fmac_f32_e32 v100, v35, v51
	v_fmac_f32_e32 v101, v35, v59
	v_fmac_f32_e32 v102, v35, v67
	v_fmac_f32_e32 v103, v35, v75
	v_fmac_f32_e32 v104, v35, v83
	s_waitcnt vmcnt(11)
	v_fmac_f32_e32 v100, v36, v52
	v_fmac_f32_e32 v101, v36, v60
	v_fmac_f32_e32 v102, v36, v68
	v_fmac_f32_e32 v103, v36, v76
	v_fmac_f32_e32 v104, v36, v84
	s_waitcnt vmcnt(10)
	v_fmac_f32_e32 v100, v37, v53
	v_fmac_f32_e32 v101, v37, v61
	v_fmac_f32_e32 v102, v37, v69
	v_fmac_f32_e32 v103, v37, v77
	v_fmac_f32_e32 v104, v37, v85
	s_waitcnt vmcnt(9)
	v_fmac_f32_e32 v100, v38, v54
	v_fmac_f32_e32 v101, v38, v62
	v_fmac_f32_e32 v102, v38, v70
	v_fmac_f32_e32 v103, v38, v78
	v_fmac_f32_e32 v104, v38, v86
	s_waitcnt vmcnt(8)
	v_fmac_f32_e32 v100, v39, v55
	v_fmac_f32_e32 v101, v39, v63
	v_fmac_f32_e32 v102, v39, v71
	v_fmac_f32_e32 v103, v39, v79
	v_fmac_f32_e32 v104, v39, v87
	ds_read_b128 v[48:51], v3 offset:96
	ds_read_b128 v[52:55], v3 offset:112
	ds_read_b128 v[56:59], v3 offset:224
	ds_read_b128 v[60:63], v3 offset:240
	ds_read_b128 v[64:67], v3 offset:352
	ds_read_b128 v[68:71], v3 offset:368
	ds_read_b128 v[72:75], v3 offset:480
	ds_read_b128 v[76:79], v3 offset:496
	ds_read_b128 v[80:83], v3 offset:608
	ds_read_b128 v[84:87], v3 offset:624
	s_waitcnt lgkmcnt(0)
	s_waitcnt vmcnt(7)
	v_fmac_f32_e32 v100, v40, v48
	v_fmac_f32_e32 v101, v40, v56
	v_fmac_f32_e32 v102, v40, v64
	v_fmac_f32_e32 v103, v40, v72
	v_fmac_f32_e32 v104, v40, v80
	s_waitcnt vmcnt(6)
	v_fmac_f32_e32 v100, v41, v49
	v_fmac_f32_e32 v101, v41, v57
	v_fmac_f32_e32 v102, v41, v65
	v_fmac_f32_e32 v103, v41, v73
	v_fmac_f32_e32 v104, v41, v81
	s_waitcnt vmcnt(5)
	v_fmac_f32_e32 v100, v42, v50
	v_fmac_f32_e32 v101, v42, v58
	v_fmac_f32_e32 v102, v42, v66
	v_fmac_f32_e32 v103, v42, v74
	v_fmac_f32_e32 v104, v42, v82
	s_waitcnt vmcnt(4)
	v_fmac_f32_e32 v100, v43, v51
	v_fmac_f32_e32 v101, v43, v59
	v_fmac_f32_e32 v102, v43, v67
	v_fmac_f32_e32 v103, v43, v75
	v_fmac_f32_e32 v104, v43, v83
	s_waitcnt vmcnt(3)
	v_fmac_f32_e32 v100, v44, v52
	v_fmac_f32_e32 v101, v44, v60
	v_fmac_f32_e32 v102, v44, v68
	v_fmac_f32_e32 v103, v44, v76
	v_fmac_f32_e32 v104, v44, v84
	s_waitcnt vmcnt(2)
	v_fmac_f32_e32 v100, v45, v53
	v_fmac_f32_e32 v101, v45, v61
	v_fmac_f32_e32 v102, v45, v69
	v_fmac_f32_e32 v103, v45, v77
	v_fmac_f32_e32 v104, v45, v85
	s_waitcnt vmcnt(1)
	v_fmac_f32_e32 v100, v46, v54
	v_fmac_f32_e32 v101, v46, v62
	v_fmac_f32_e32 v102, v46, v70
	v_fmac_f32_e32 v103, v46, v78
	v_fmac_f32_e32 v104, v46, v86
	s_waitcnt vmcnt(0)
	v_fmac_f32_e32 v100, v47, v55
	v_fmac_f32_e32 v101, v47, v63
	v_fmac_f32_e32 v102, v47, v71
	v_fmac_f32_e32 v103, v47, v79
	v_fmac_f32_e32 v104, v47, v87
	s_lshl_b32 s17, s29, 1
	s_add_i32 s17, s17, s16
	s_mul_i32 s17, s17, 0x1e000
	s_add_u32 s26, s10, s17
	s_addc_u32 s27, s11, 0
	global_store_dword v10, v100, s[26:27]
	s_add_u32 s26, s26, 0x6000
	s_addc_u32 s27, s27, 0
	global_store_dword v10, v101, s[26:27]
	s_add_u32 s26, s26, 0x6000
	s_addc_u32 s27, s27, 0
	global_store_dword v10, v102, s[26:27]
	s_add_u32 s26, s26, 0x6000
	s_addc_u32 s27, s27, 0
	global_store_dword v10, v103, s[26:27]
	s_add_u32 s26, s26, 0x6000
	s_addc_u32 s27, s27, 0
	global_store_dword v10, v104, s[26:27]
	s_add_i32 s28, s28, s42
	s_cmpk_gt_i32 s28, 0x2ff
	s_cbranch_scc0 .LBB0_8
